# static s_setprio 1 for waves 4-7 also around the phase 8 K-loop (flips deleted there too)
# speedup vs baseline: 1.0010x; 1.0010x over previous
; #define PG8_STAGE(bufoff, gbase, voff) do { _Pragma("unroll") for (int _i = 0; _i < 2; ++_i) \
;         __builtin_amdgcn_global_load_lds((const unsigned*)((const char*)(gbase) + (voff)[_i]), (LAS unsigned*)(lds + (bufoff) + ldsw + _i * 8192), 16, 0, 0); } while (0)
; #define PG8_LDA(dst, b, h) do { _Pragma("unroll") for (int m = 0; m < 4; ++m) _Pragma("unroll") for (int k = 0; k < 2; ++k) dst[m][k] = *(const LAS bf16x8*)(lds + PG8_SA(b, h) + aoff + m * 2048 + k * 1024); } while (0)
; #define PG8_LDB(dst, b, h) do { _Pragma("unroll") for (int n = 0; n < 2; ++n) _Pragma("unroll") for (int k = 0; k < 2; ++k) dst[n][k] = *(const LAS bf16x8*)(lds + PG8_SB(b, h) + boff + n * 2048 + k * 1024); } while (0)
; #define PG8_MMA(ai, bj, At, Bt) do { __builtin_amdgcn_s_setprio(1); _Pragma("unroll") for (int m = 0; m < 4; ++m) _Pragma("unroll") for (int n = 0; n < 2; ++n) _Pragma("unroll") for (int k = 0; k < 2; ++k) \
;         acc[ai][bj][m][n] = __builtin_amdgcn_mfma_f32_16x16x32_bf16(Bt[n][k], At[m][k], acc[ai][bj][m][n], 0, 0, 0); __builtin_amdgcn_s_setprio(0); } while (0)
; #define PG8_WAIT_V(n) asm volatile("s_waitcnt vmcnt(" #n ")" ::: "memory")
; #define PG8_WAIT_L(n) asm volatile("s_waitcnt lgkmcnt(" #n ")" ::: "memory")
; template <class Epi, class Sched>
; __device__ __forceinline__ void gemm_phase(LAS unsigned char* lds, const Gemm g, const Sched& S, const Epi& E) {
;     ...
;             PG8_LDB(B0, 0, 0); PG8_SCHED; PG8_LDA(At, 0, 0); PG8_STAGE(PG8_SA(1, 1), a1 + hstepA, voffA);
;             PG8_WAIT_L(8); PG8_BAR; PG8_WAIT_L(0); PG8_MMA(0, 0, At, B0); PG8_BAR; PG8_SCHED;
;             PG8_LDB(B1, 0, 1); PG8_STAGE(PG8_SB(0, 0), b2, voffB);
;             PG8_BAR; PG8_WAIT_L(0); if constexpr (!Epi::DIAG) PG8_MMA(0, 1, At, B1); PG8_BAR;
;             PG8_LDA(At, 0, 1); PG8_STAGE(PG8_SA(0, 0), a2, voffA);
;             PG8_BAR; PG8_WAIT_L(0); if constexpr (!Epi::DIAG) PG8_MMA(1, 0, At, B0); PG8_BAR; PG8_SCHED;
;             PG8_STAGE(PG8_SB(0, 1), b2 + hstepB, voffB);
;             PG8_WAIT_V(6); PG8_BAR; PG8_MMA(1, 1, At, B1); PG8_BAR;
;     ...
;         for (int a = 0; a < 2; ++a)
; #pragma unroll
;             for (int b = 0; b < 2; ++b)
; #pragma unroll
;                 for (int m = 0; m < 4; ++m)
; #pragma unroll
;                     for (int n = 0; n < 2; ++n) acc[a][b][m][n] = (f32x4){0.f, 0.f, 0.f, 0.f};
;         cur = nxt; cA = nA; cB = nB; ++ui;
.LBB0_1384:
	s_ashr_i32 s19, s18, 31
	v_cmp_lt_i64_e32 vcc, s[20:21], v[76:77]
	s_lshl_b64 s[20:21], s[18:19], 19
	s_add_u32 s20, s30, s20
	s_addc_u32 s21, s31, s21
	s_and_b64 s[22:23], vcc, exec
	s_cselect_b32 s19, s21, s27
	s_cselect_b32 s52, s20, s26
	s_ashr_i32 s17, s16, 31
	s_lshl_b64 s[22:23], s[16:17], 19
	s_add_u32 s22, s34, s22
	s_addc_u32 s23, s35, s23
	s_and_b64 s[54:55], vcc, exec
	s_cselect_b32 s17, s23, s29
	s_cselect_b32 s53, s22, s28
	s_add_u32 s26, s26, 0x880
	s_addc_u32 s27, s27, 0
	s_add_u32 s28, s28, 0x100
	v_mov_b32_e32 v0, 0
	s_addc_u32 s29, s29, 0
	s_mov_b32 s54, -2
	v_mov_b32_e32 v1, v0
	v_mov_b32_e32 v2, v0
	v_mov_b32_e32 v3, v0
	v_mov_b32_e32 v8, v0
	v_mov_b32_e32 v9, v0
	v_mov_b32_e32 v10, v0
	v_mov_b32_e32 v11, v0
	v_mov_b32_e32 v16, v0
	v_mov_b32_e32 v17, v0
	v_mov_b32_e32 v18, v0
	v_mov_b32_e32 v19, v0
	v_mov_b32_e32 v24, v0
	v_mov_b32_e32 v25, v0
	v_mov_b32_e32 v26, v0
	v_mov_b32_e32 v27, v0
	v_mov_b32_e32 v32, v0
	v_mov_b32_e32 v33, v0
	v_mov_b32_e32 v34, v0
	v_mov_b32_e32 v35, v0
	v_mov_b32_e32 v36, v0
	v_mov_b32_e32 v37, v0
	v_mov_b32_e32 v38, v0
	v_mov_b32_e32 v39, v0
	v_mov_b32_e32 v48, v0
	v_mov_b32_e32 v49, v0
	v_mov_b32_e32 v50, v0
	v_mov_b32_e32 v51, v0
	v_mov_b32_e32 v52, v0
	v_mov_b32_e32 v53, v0
	v_mov_b32_e32 v54, v0
	v_mov_b32_e32 v55, v0
	v_mov_b32_e32 v4, v0
	v_mov_b32_e32 v5, v0
	v_mov_b32_e32 v6, v0
	v_mov_b32_e32 v7, v0
	v_mov_b32_e32 v12, v0
	v_mov_b32_e32 v13, v0
	v_mov_b32_e32 v14, v0
	v_mov_b32_e32 v15, v0
	v_mov_b32_e32 v20, v0
	v_mov_b32_e32 v21, v0
	v_mov_b32_e32 v22, v0
	v_mov_b32_e32 v23, v0
	v_mov_b32_e32 v28, v0
	v_mov_b32_e32 v29, v0
	v_mov_b32_e32 v30, v0
	v_mov_b32_e32 v31, v0
	v_mov_b32_e32 v40, v0
	v_mov_b32_e32 v41, v0
	v_mov_b32_e32 v42, v0
	v_mov_b32_e32 v43, v0
	v_mov_b32_e32 v44, v0
	v_mov_b32_e32 v45, v0
	v_mov_b32_e32 v46, v0
	v_mov_b32_e32 v47, v0
	v_mov_b32_e32 v56, v0
	v_mov_b32_e32 v57, v0
	v_mov_b32_e32 v58, v0
	v_mov_b32_e32 v59, v0
	v_mov_b32_e32 v60, v0
	v_mov_b32_e32 v61, v0
	v_mov_b32_e32 v62, v0
	v_mov_b32_e32 v63, v0
	s_mov_b32 s62, s63
	s_lshr_b32 s72, s3, 8
	s_cmp_lg_u32 s72, 0
	s_cbranch_scc0 .Lprio_1385
	s_setprio 1
.Lprio_1385:
.LBB0_1385:
	ds_read_b128 v[80:83], v91
	ds_read_b128 v[94:97], v219
	ds_read_b128 v[98:101], v91 offset:2048
	ds_read_b128 v[102:105], v219 offset:2048
	s_add_u32 s60, s62, 0x100
	s_and_b32 s60, s60, 0x7ff
	s_add_u32 s55, s26, s60
	s_addc_u32 s56, s27, 0
	s_sub_u32 s55, s55, 0x880
	s_subb_u32 s56, s56, 0
	s_add_u32 s64, s28, s60
	s_addc_u32 s65, s29, 0
	s_sub_u32 s64, s64, 0x100
	s_subb_u32 s65, s65, 0
	s_add_u32 s66, s52, s63
	s_addc_u32 s67, s19, 0
	s_add_u32 s68, s53, s63
	s_addc_u32 s69, s17, 0
	s_cmp_eq_u32 s54, 12
	s_cselect_b32 s57, s67, s56
	s_cselect_b32 s56, s66, s55
	s_cselect_b32 s59, s69, s65
	s_cselect_b32 s58, s68, s64
	ds_read_b128 v[106:109], v92
	ds_read_b128 v[110:113], v218
	ds_read_b128 v[114:117], v92 offset:2048
	ds_read_b128 v[118:121], v218 offset:2048
	ds_read_b128 v[122:125], v92 offset:4096
	ds_read_b128 v[126:129], v218 offset:4096
	ds_read_b128 v[130:133], v92 offset:6144
	ds_read_b128 v[134:137], v218 offset:6144
	s_add_u32 s60, s28, 0x780
	s_addc_u32 s61, s29, 0
	s_add_u32 s60, s60, s62
	s_addc_u32 s61, s61, 0
	s_add_u32 s70, s26, s62
	s_addc_u32 s71, s27, 0
	v_lshl_add_u64 v[84:85], s[60:61], 0, v[66:67]
	s_add_i32 m0, s36, 0x1c000
	s_nop 0
	global_load_lds_dwordx4 v[84:85], off
	v_lshl_add_u64 v[84:85], s[60:61], 0, v[70:71]
	s_add_i32 m0, s36, 0x1e000
	s_nop 0
	global_load_lds_dwordx4 v[84:85], off
	v_lshl_add_u64 v[84:85], s[70:71], 0, v[74:75]
	s_add_i32 m0, s25, 0xc000
	s_nop 0
	global_load_lds_dwordx4 v[84:85], off
	v_lshl_add_u64 v[84:85], s[70:71], 0, v[72:73]
	s_add_i32 m0, s25, 0xe000
	s_nop 0
	global_load_lds_dwordx4 v[84:85], off
	s_waitcnt vmcnt(8)
	s_waitcnt lgkmcnt(0)
	s_barrier
	v_mfma_f32_16x16x32_bf16 v[60:63], v[80:83], v[106:109], v[60:63]
	v_mfma_f32_16x16x32_bf16 v[56:59], v[98:101], v[106:109], v[56:59]
	v_mfma_f32_16x16x32_bf16 v[44:47], v[80:83], v[114:117], v[44:47]
	v_mfma_f32_16x16x32_bf16 v[40:43], v[98:101], v[114:117], v[40:43]
	v_mfma_f32_16x16x32_bf16 v[28:31], v[80:83], v[122:125], v[28:31]
	v_mfma_f32_16x16x32_bf16 v[20:23], v[98:101], v[122:125], v[20:23]
	v_mfma_f32_16x16x32_bf16 v[12:15], v[80:83], v[130:133], v[12:15]
	v_mfma_f32_16x16x32_bf16 v[4:7], v[98:101], v[130:133], v[4:7]
	v_mfma_f32_16x16x32_bf16 v[60:63], v[94:97], v[110:113], v[60:63]
	v_mfma_f32_16x16x32_bf16 v[56:59], v[102:105], v[110:113], v[56:59]
	v_mfma_f32_16x16x32_bf16 v[44:47], v[94:97], v[118:121], v[44:47]
	v_mfma_f32_16x16x32_bf16 v[40:43], v[102:105], v[118:121], v[40:43]
	v_mfma_f32_16x16x32_bf16 v[28:31], v[94:97], v[126:129], v[28:31]
	v_mfma_f32_16x16x32_bf16 v[20:23], v[102:105], v[126:129], v[20:23]
	v_mfma_f32_16x16x32_bf16 v[12:15], v[94:97], v[134:137], v[12:15]
	v_mfma_f32_16x16x32_bf16 v[4:7], v[102:105], v[134:137], v[4:7]
	s_barrier
	ds_read_b128 v[80:83], v91 offset:16384
	ds_read_b128 v[94:97], v219 offset:16384
	ds_read_b128 v[98:101], v91 offset:18432
	ds_read_b128 v[102:105], v219 offset:18432
	ds_read_b128 v[106:109], v92 offset:16384
	ds_read_b128 v[110:113], v218 offset:16384
	ds_read_b128 v[114:117], v92 offset:18432
	ds_read_b128 v[118:121], v218 offset:18432
	ds_read_b128 v[122:125], v92 offset:20480
	ds_read_b128 v[126:129], v218 offset:20480
	ds_read_b128 v[130:133], v92 offset:22528
	ds_read_b128 v[134:137], v218 offset:22528
	s_add_i32 s55, s47, s36
	v_lshl_add_u64 v[84:85], s[58:59], 0, v[66:67]
	s_mov_b32 m0, s55
	s_nop 0
	global_load_lds_dwordx4 v[84:85], off
	v_lshl_add_u64 v[138:139], s[58:59], 0, v[70:71]
	s_add_i32 m0, s55, 0x2000
	s_nop 0
	global_load_lds_dwordx4 v[138:139], off
	v_lshl_add_u64 v[140:141], s[56:57], 0, v[64:65]
	s_mov_b32 m0, s25
	s_nop 0
	global_load_lds_dwordx4 v[140:141], off
	v_lshl_add_u64 v[142:143], s[56:57], 0, v[68:69]
	s_mov_b32 m0, s39
	s_nop 0
	global_load_lds_dwordx4 v[142:143], off
	s_waitcnt vmcnt(8)
	s_waitcnt lgkmcnt(0)
	s_barrier
; #define PG8_STAGE(bufoff, gbase, voff) do { _Pragma("unroll") for (int _i = 0; _i < 2; ++_i) \
;         __builtin_amdgcn_global_load_lds((const unsigned*)((const char*)(gbase) + (voff)[_i]), (LAS unsigned*)(lds + (bufoff) + ldsw + _i * 8192), 16, 0, 0); } while (0)
; #define PG8_LDA(dst, b, h) do { _Pragma("unroll") for (int m = 0; m < 4; ++m) _Pragma("unroll") for (int k = 0; k < 2; ++k) dst[m][k] = *(const LAS bf16x8*)(lds + PG8_SA(b, h) + aoff + m * 2048 + k * 1024); } while (0)
; #define PG8_LDB(dst, b, h) do { _Pragma("unroll") for (int n = 0; n < 2; ++n) _Pragma("unroll") for (int k = 0; k < 2; ++k) dst[n][k] = *(const LAS bf16x8*)(lds + PG8_SB(b, h) + boff + n * 2048 + k * 1024); } while (0)
; #define PG8_MMA(ai, bj, At, Bt) do { __builtin_amdgcn_s_setprio(1); _Pragma("unroll") for (int m = 0; m < 4; ++m) _Pragma("unroll") for (int n = 0; n < 2; ++n) _Pragma("unroll") for (int k = 0; k < 2; ++k) \
;         acc[ai][bj][m][n] = __builtin_amdgcn_mfma_f32_16x16x32_bf16(Bt[n][k], At[m][k], acc[ai][bj][m][n], 0, 0, 0); __builtin_amdgcn_s_setprio(0); } while (0)
; #define PG8_WAIT_V(n) asm volatile("s_waitcnt vmcnt(" #n ")" ::: "memory")
; #define PG8_WAIT_L(n) asm volatile("s_waitcnt lgkmcnt(" #n ")" ::: "memory")
; #define PG8_BAR __builtin_amdgcn_s_barrier()
; #define PG8_SCHED __builtin_amdgcn_sched_barrier(0)
; template <class Epi, class Sched>
; __device__ __forceinline__ void gemm_phase(LAS unsigned char* lds, const Gemm g, const Sched& S, const Epi& E) {
;     ...
;             PG8_WAIT_V(6); PG8_BAR; PG8_MMA(1, 1, At, B1); PG8_BAR;
;             PG8_LDB(B0, 1, 0); PG8_SCHED; PG8_LDA(At, 1, 0); PG8_STAGE(PG8_SA(0, 1), a2 + hstepA, voffA);
;             PG8_WAIT_L(8); PG8_BAR; PG8_WAIT_L(0); PG8_MMA(0, 0, At, B0); PG8_BAR; PG8_SCHED;
;             PG8_LDB(B1, 1, 1); PG8_STAGE(PG8_SB(1, 0), b3, voffB);
;             PG8_BAR; PG8_WAIT_L(0); if constexpr (!Epi::DIAG) PG8_MMA(0, 1, At, B1); PG8_BAR;
;             PG8_LDA(At, 1, 1); PG8_STAGE(PG8_SA(1, 0), a3, voffA);
;             PG8_BAR; PG8_WAIT_L(0); if constexpr (!Epi::DIAG) PG8_MMA(1, 0, At, B0); PG8_BAR; PG8_SCHED;
;             PG8_STAGE(PG8_SB(1, 1), b3 + hstepB, voffB);
;             PG8_WAIT_V(6); PG8_BAR; PG8_MMA(1, 1, At, B1); PG8_BAR;
	v_mfma_f32_16x16x32_bf16 v[52:55], v[80:83], v[106:109], v[52:55]
	v_mfma_f32_16x16x32_bf16 v[48:51], v[98:101], v[106:109], v[48:51]
	v_mfma_f32_16x16x32_bf16 v[36:39], v[80:83], v[114:117], v[36:39]
	v_mfma_f32_16x16x32_bf16 v[32:35], v[98:101], v[114:117], v[32:35]
	v_mfma_f32_16x16x32_bf16 v[24:27], v[80:83], v[122:125], v[24:27]
	v_mfma_f32_16x16x32_bf16 v[16:19], v[98:101], v[122:125], v[16:19]
	v_mfma_f32_16x16x32_bf16 v[8:11], v[80:83], v[130:133], v[8:11]
	v_mfma_f32_16x16x32_bf16 v[0:3], v[98:101], v[130:133], v[0:3]
	v_mfma_f32_16x16x32_bf16 v[52:55], v[94:97], v[110:113], v[52:55]
	v_mfma_f32_16x16x32_bf16 v[48:51], v[102:105], v[110:113], v[48:51]
	v_mfma_f32_16x16x32_bf16 v[36:39], v[94:97], v[118:121], v[36:39]
	v_mfma_f32_16x16x32_bf16 v[32:35], v[102:105], v[118:121], v[32:35]
	v_mfma_f32_16x16x32_bf16 v[24:27], v[94:97], v[126:129], v[24:27]
	v_mfma_f32_16x16x32_bf16 v[16:19], v[102:105], v[126:129], v[16:19]
	v_mfma_f32_16x16x32_bf16 v[8:11], v[94:97], v[134:137], v[8:11]
	v_mfma_f32_16x16x32_bf16 v[0:3], v[102:105], v[134:137], v[0:3]
	s_barrier
	ds_read_b128 v[80:83], v91 offset:32768
	ds_read_b128 v[94:97], v219 offset:32768
	ds_read_b128 v[98:101], v91 offset:34816
	ds_read_b128 v[102:105], v219 offset:34816
	ds_read_b128 v[106:109], v92 offset:32768
	ds_read_b128 v[110:113], v218 offset:32768
	ds_read_b128 v[114:117], v92 offset:34816
	ds_read_b128 v[118:121], v218 offset:34816
	ds_read_b128 v[122:125], v92 offset:36864
	ds_read_b128 v[126:129], v218 offset:36864
	ds_read_b128 v[130:133], v92 offset:38912
	ds_read_b128 v[134:137], v218 offset:38912
	s_add_i32 s55, s48, s36
	v_lshl_add_u64 v[144:145], v[84:85], 0, s[4:5]
	s_mov_b32 m0, s55
	s_nop 0
	global_load_lds_dwordx4 v[144:145], off
	v_lshl_add_u64 v[144:145], v[138:139], 0, s[4:5]
	s_add_i32 m0, s55, 0x2000
	s_nop 0
	global_load_lds_dwordx4 v[144:145], off
	v_lshl_add_u64 v[144:145], v[140:141], 0, s[4:5]
	s_mov_b32 m0, s40
	s_nop 0
	global_load_lds_dwordx4 v[144:145], off
	v_lshl_add_u64 v[144:145], v[142:143], 0, s[4:5]
	s_mov_b32 m0, s41
	s_nop 0
	global_load_lds_dwordx4 v[144:145], off
	s_waitcnt vmcnt(8)
	s_waitcnt lgkmcnt(0)
	s_barrier
	v_mfma_f32_16x16x32_bf16 v[60:63], v[80:83], v[106:109], v[60:63]
	v_mfma_f32_16x16x32_bf16 v[56:59], v[98:101], v[106:109], v[56:59]
	v_mfma_f32_16x16x32_bf16 v[44:47], v[80:83], v[114:117], v[44:47]
	v_mfma_f32_16x16x32_bf16 v[40:43], v[98:101], v[114:117], v[40:43]
	v_mfma_f32_16x16x32_bf16 v[28:31], v[80:83], v[122:125], v[28:31]
	v_mfma_f32_16x16x32_bf16 v[20:23], v[98:101], v[122:125], v[20:23]
	v_mfma_f32_16x16x32_bf16 v[12:15], v[80:83], v[130:133], v[12:15]
	v_mfma_f32_16x16x32_bf16 v[4:7], v[98:101], v[130:133], v[4:7]
	v_mfma_f32_16x16x32_bf16 v[60:63], v[94:97], v[110:113], v[60:63]
	v_mfma_f32_16x16x32_bf16 v[56:59], v[102:105], v[110:113], v[56:59]
	v_mfma_f32_16x16x32_bf16 v[44:47], v[94:97], v[118:121], v[44:47]
	v_mfma_f32_16x16x32_bf16 v[40:43], v[102:105], v[118:121], v[40:43]
	v_mfma_f32_16x16x32_bf16 v[28:31], v[94:97], v[126:129], v[28:31]
	v_mfma_f32_16x16x32_bf16 v[20:23], v[102:105], v[126:129], v[20:23]
	v_mfma_f32_16x16x32_bf16 v[12:15], v[94:97], v[134:137], v[12:15]
	v_mfma_f32_16x16x32_bf16 v[4:7], v[102:105], v[134:137], v[4:7]
	s_barrier
	ds_read_b128 v[80:83], v91 offset:49152
	ds_read_b128 v[94:97], v219 offset:49152
	ds_read_b128 v[98:101], v91 offset:51200
	ds_read_b128 v[102:105], v219 offset:51200
	ds_read_b128 v[106:109], v92 offset:49152
	ds_read_b128 v[110:113], v218 offset:49152
	ds_read_b128 v[114:117], v92 offset:51200
	ds_read_b128 v[118:121], v218 offset:51200
	ds_read_b128 v[122:125], v92 offset:53248
	ds_read_b128 v[126:129], v218 offset:53248
	ds_read_b128 v[130:133], v92 offset:55296
	ds_read_b128 v[134:137], v218 offset:55296
	s_add_i32 s55, s36, 0x18000
	v_lshl_add_u64 v[144:145], v[84:85], 0, s[12:13]
	s_mov_b32 m0, s55
	s_nop 0
	global_load_lds_dwordx4 v[144:145], off
	v_lshl_add_u64 v[144:145], v[138:139], 0, s[12:13]
	s_add_i32 m0, s55, 0x2000
	s_nop 0
	global_load_lds_dwordx4 v[144:145], off
	v_lshl_add_u64 v[144:145], v[140:141], 0, s[12:13]
	s_mov_b32 m0, s44
	s_nop 0
	global_load_lds_dwordx4 v[144:145], off
	v_lshl_add_u64 v[144:145], v[142:143], 0, s[12:13]
	s_mov_b32 m0, s45
	s_nop 0
	global_load_lds_dwordx4 v[144:145], off
	s_waitcnt vmcnt(8)
	s_waitcnt lgkmcnt(0)
	s_barrier
	v_mfma_f32_16x16x32_bf16 v[52:55], v[80:83], v[106:109], v[52:55]
	v_mfma_f32_16x16x32_bf16 v[48:51], v[98:101], v[106:109], v[48:51]
	v_mfma_f32_16x16x32_bf16 v[36:39], v[80:83], v[114:117], v[36:39]
	v_mfma_f32_16x16x32_bf16 v[32:35], v[98:101], v[114:117], v[32:35]
	v_mfma_f32_16x16x32_bf16 v[24:27], v[80:83], v[122:125], v[24:27]
	v_mfma_f32_16x16x32_bf16 v[16:19], v[98:101], v[122:125], v[16:19]
	v_mfma_f32_16x16x32_bf16 v[8:11], v[80:83], v[130:133], v[8:11]
	v_mfma_f32_16x16x32_bf16 v[0:3], v[98:101], v[130:133], v[0:3]
	v_mfma_f32_16x16x32_bf16 v[52:55], v[94:97], v[110:113], v[52:55]
	v_mfma_f32_16x16x32_bf16 v[48:51], v[102:105], v[110:113], v[48:51]
	v_mfma_f32_16x16x32_bf16 v[36:39], v[94:97], v[118:121], v[36:39]
	v_mfma_f32_16x16x32_bf16 v[32:35], v[102:105], v[118:121], v[32:35]
	v_mfma_f32_16x16x32_bf16 v[24:27], v[94:97], v[126:129], v[24:27]
	v_mfma_f32_16x16x32_bf16 v[16:19], v[102:105], v[126:129], v[16:19]
	v_mfma_f32_16x16x32_bf16 v[8:11], v[94:97], v[134:137], v[8:11]
	v_mfma_f32_16x16x32_bf16 v[0:3], v[102:105], v[134:137], v[0:3]
	s_add_i32 s54, s54, 2
	s_add_u32 s62, s62, 0x100
	s_and_b32 s62, s62, 0x7ff
	s_cmp_gt_u32 s54, 13
	s_barrier
	s_cbranch_scc0 .LBB0_1385
; __device__ __forceinline__ u32x4 pack8(const float* f) { u32x4 w; w.x = pk2(f[0], f[1]); w.y = pk2(f[2], f[3]); w.z = pk2(f[4], f[5]); w.w = pk2(f[6], f[7]); return w; }
;     __device__ __forceinline__ void operator()(const Acc& acc, const Unit& u, int wr, int wc, int fr, int fq) const { if (u.piece == 0) e1(acc, u, wr, wc, fr, fq); else e2(acc, u, wr, wc, fr, fq); }
;     __device__ __forceinline__ void operator()(const Acc& acc, const Unit& u, int wr, int wc, int fr, int fq) const {
;         const int row0 = u.pm * HALF + wr * 64 + fr, col0 = u.pn * HALF + wc * 32 + 8 * fq;
; #pragma unroll
;         for (int m = 0; m < 4; ++m) { const size_t row = (size_t)(row0 + m * 16); const bf16_t* pr = proj + row * NPROJ + col0;
;             float ga[8], gb[8], v[8]; unpack8(*(const u32x4*)(pr + C_GA), ga); unpack8(*(const u32x4*)(pr + C_GB), gb);
; #pragma unroll
;             for (int n = 0; n < 2; ++n) {
;                 const f32x4 A4 = {ga[4 * n], ga[4 * n + 1], ga[4 * n + 2], ga[4 * n + 3]}, B4 = {gb[4 * n], gb[4 * n + 1], gb[4 * n + 2], gb[4 * n + 3]};
;                 const f32x4 aa = A4 * (-1.4426950408889634f), ab = B4 * (-1.4426950408889634f);
;                 f32x4 ta, tb;
; #pragma unroll
;                 for (int j = 0; j < 4; ++j) { ta[j] = __builtin_amdgcn_exp2f(aa[j]); tb[j] = __builtin_amdgcn_exp2f(ab[j]); }
;                 ta = ta + 1.0f; tb = tb + 1.0f;
; #pragma unroll
;                 for (int j = 0; j < 4; ++j) { ta[j] = __builtin_amdgcn_rcpf(ta[j]); tb[j] = __builtin_amdgcn_rcpf(tb[j]); }
;                 const f32x4 r = acc[0][0][m][n] * ta + acc[1][1][m][n] * tb;
; #pragma unroll
;                 for (int j = 0; j < 4; ++j) v[4 * n + j] = r[j]; }
;             *(u32x4*)(O + row * DM + col0) = pack8(v); }
	s_setprio 0
	v_lshl_or_b32 v80, s51, 7, v90
	v_lshl_add_u32 v82, s24, 7, v88
	v_ashrrev_i32_e32 v81, 31, v80
	v_mov_b64_e32 v[84:85], s[10:11]
	v_mad_i64_i32 v[94:95], s[26:27], v82, s49, v[84:85]
	v_lshlrev_b64 v[80:81], 1, v[80:81]
	v_lshl_add_u64 v[98:99], v[94:95], 0, v[80:81]
	v_add_co_u32_e32 v94, vcc, 0x2000, v98
	v_ashrrev_i32_e32 v83, 31, v82
	s_nop 0
	v_addc_co_u32_e32 v95, vcc, 0, v99, vcc
	v_add_co_u32_e32 v98, vcc, s50, v98
	global_load_dwordx4 v[94:97], v[94:95], off offset:2048
	s_nop 0
	v_addc_co_u32_e32 v99, vcc, 0, v99, vcc
	global_load_dwordx4 v[98:101], v[98:99], off offset:2048
	v_or_b32_e32 v210, 16, v82
	v_mad_i64_i32 v[212:213], s[26:27], v210, s49, v[84:85]
	v_lshl_add_u64 v[212:213], v[212:213], 0, v[80:81]
	v_add_co_u32_e32 v214, vcc, s42, v212
	s_nop 1
	v_addc_co_u32_e32 v215, vcc, 0, v213, vcc
	v_add_co_u32_e32 v212, vcc, s50, v212
	s_nop 1
	v_addc_co_u32_e32 v213, vcc, 0, v213, vcc
	global_load_dwordx4 v[186:189], v[214:215], off offset:2048
	global_load_dwordx4 v[190:193], v[212:213], off offset:2048
	v_or_b32_e32 v210, 32, v82
	v_mad_i64_i32 v[212:213], s[26:27], v210, s49, v[84:85]
	v_lshl_add_u64 v[212:213], v[212:213], 0, v[80:81]
	v_add_co_u32_e32 v214, vcc, s42, v212
	s_nop 1
	v_addc_co_u32_e32 v215, vcc, 0, v213, vcc
	v_add_co_u32_e32 v212, vcc, s50, v212
	s_nop 1
	v_addc_co_u32_e32 v213, vcc, 0, v213, vcc
	global_load_dwordx4 v[194:197], v[214:215], off offset:2048
	global_load_dwordx4 v[198:201], v[212:213], off offset:2048
	v_or_b32_e32 v210, 48, v82
	v_mad_i64_i32 v[212:213], s[26:27], v210, s49, v[84:85]
	v_lshl_add_u64 v[212:213], v[212:213], 0, v[80:81]
	v_add_co_u32_e32 v214, vcc, s42, v212
	s_nop 1
	v_addc_co_u32_e32 v215, vcc, 0, v213, vcc
	v_add_co_u32_e32 v212, vcc, s50, v212
	s_nop 1
	v_addc_co_u32_e32 v213, vcc, 0, v213, vcc
	global_load_dwordx4 v[202:205], v[214:215], off offset:2048
	global_load_dwordx4 v[206:209], v[212:213], off offset:2048
	s_mov_b32 s51, s16
	s_mov_b32 s24, s18
	s_mov_b64 s[28:29], s[22:23]
	s_waitcnt vmcnt(6)
	v_lshlrev_b32_e32 v102, 16, v94
	v_and_b32_e32 v94, 0xffff0000, v94
	v_lshlrev_b32_e32 v103, 16, v95
	v_and_b32_e32 v95, 0xffff0000, v95
	v_lshlrev_b32_e32 v104, 16, v96
	v_and_b32_e32 v96, 0xffff0000, v96
	v_lshlrev_b32_e32 v106, 16, v98
	v_and_b32_e32 v98, 0xffff0000, v98
	v_lshlrev_b32_e32 v105, 16, v97
	v_and_b32_e32 v97, 0xffff0000, v97
	v_lshlrev_b32_e32 v107, 16, v99
	v_and_b32_e32 v99, 0xffff0000, v99
	v_lshlrev_b32_e32 v108, 16, v100
	v_and_b32_e32 v100, 0xffff0000, v100
	v_lshlrev_b32_e32 v109, 16, v101
	v_and_b32_e32 v110, 0xffff0000, v101
	v_mul_f32_e32 v101, 0xbfb8aa3b, v102
	v_mul_f32_e32 v102, 0xbfb8aa3b, v94
	v_mul_f32_e32 v103, 0xbfb8aa3b, v103
	v_mul_f32_e32 v111, 0xbfb8aa3b, v95
	v_mul_f32_e32 v112, 0xbfb8aa3b, v96
	v_mul_f32_e32 v106, 0xbfb8aa3b, v106
	v_mul_f32_e32 v114, 0xbfb8aa3b, v98
	v_mul_f32_e32 v104, 0xbfb8aa3b, v104
	v_mul_f32_e32 v113, 0xbfb8aa3b, v97
	v_exp_f32_e32 v95, v102
	v_exp_f32_e32 v96, v103
	v_mul_f32_e32 v107, 0xbfb8aa3b, v107
	v_exp_f32_e32 v97, v111
	v_mul_f32_e32 v111, 0xbfb8aa3b, v99
	v_mul_f32_e32 v108, 0xbfb8aa3b, v108
	v_exp_f32_e32 v99, v112
	v_mul_f32_e32 v112, 0xbfb8aa3b, v100
	v_exp_f32_e32 v102, v106
	v_exp_f32_e32 v103, v114
	v_mul_f32_e32 v105, 0xbfb8aa3b, v105
	v_exp_f32_e32 v94, v101
	v_exp_f32_e32 v98, v104
	v_mul_f32_e32 v109, 0xbfb8aa3b, v109
	v_mul_f32_e32 v110, 0xbfb8aa3b, v110
	v_exp_f32_e32 v104, v107
	v_exp_f32_e32 v106, v108
	v_exp_f32_e32 v107, v112
	v_exp_f32_e32 v100, v105
	v_exp_f32_e32 v105, v111
	v_exp_f32_e32 v108, v109
	v_exp_f32_e32 v109, v110
	v_exp_f32_e32 v101, v113
	v_pk_add_f32 v[102:103], v[102:103], 1.0 op_sel_hi:[1,0]
	v_pk_add_f32 v[94:95], v[94:95], 1.0 op_sel_hi:[1,0]
	v_pk_add_f32 v[106:107], v[106:107], 1.0 op_sel_hi:[1,0]
	v_rcp_f32_e32 v102, v102
	v_rcp_f32_e32 v103, v103
	v_pk_add_f32 v[98:99], v[98:99], 1.0 op_sel_hi:[1,0]
	v_pk_add_f32 v[104:105], v[104:105], 1.0 op_sel_hi:[1,0]
	v_rcp_f32_e32 v94, v94
	v_rcp_f32_e32 v95, v95
	v_pk_add_f32 v[108:109], v[108:109], 1.0 op_sel_hi:[1,0]
	v_rcp_f32_e32 v106, v106
	v_rcp_f32_e32 v107, v107
	v_pk_add_f32 v[96:97], v[96:97], 1.0 op_sel_hi:[1,0]
	v_pk_add_f32 v[100:101], v[100:101], 1.0 op_sel_hi:[1,0]
	v_rcp_f32_e32 v98, v98
	v_rcp_f32_e32 v99, v99
	v_rcp_f32_e32 v104, v104
	v_rcp_f32_e32 v105, v105
	v_rcp_f32_e32 v108, v108
	v_rcp_f32_e32 v109, v109
	v_rcp_f32_e32 v96, v96
	v_rcp_f32_e32 v97, v97
	v_rcp_f32_e32 v100, v100
	v_rcp_f32_e32 v101, v101
	v_pk_mul_f32 v[52:53], v[52:53], v[102:103]
	v_pk_mul_f32 v[48:49], v[48:49], v[106:107]
	v_pk_fma_f32 v[52:53], v[60:61], v[94:95], v[52:53]
	v_pk_mul_f32 v[54:55], v[54:55], v[104:105]
	v_pk_mul_f32 v[50:51], v[50:51], v[108:109]
	v_pk_fma_f32 v[56:57], v[56:57], v[98:99], v[48:49]
	v_cvt_pk_bf16_f32 v48, v52, v53
	v_lshlrev_b64 v[52:53], 12, v[82:83]
	v_pk_fma_f32 v[54:55], v[62:63], v[96:97], v[54:55]
	v_pk_fma_f32 v[58:59], v[58:59], v[100:101], v[50:51]
	v_lshl_add_u64 v[52:53], s[8:9], 0, v[52:53]
	v_cvt_pk_bf16_f32 v49, v54, v55
	v_cvt_pk_bf16_f32 v50, v56, v57
	v_cvt_pk_bf16_f32 v51, v58, v59
	v_lshl_add_u64 v[52:53], v[52:53], 0, v[80:81]
	v_or_b32_e32 v56, 16, v82
	global_store_dwordx4 v[52:53], v[48:51], off
	v_ashrrev_i32_e32 v57, 31, v56
	s_nop 0
	v_mad_i64_i32 v[48:49], s[26:27], v56, s49, v[84:85]
	v_lshl_add_u64 v[52:53], v[48:49], 0, v[80:81]
	v_add_co_u32_e32 v48, vcc, s42, v52
	s_nop 1
	v_addc_co_u32_e32 v49, vcc, 0, v53, vcc
	v_add_co_u32_e32 v52, vcc, s50, v52
	s_waitcnt vmcnt(5)
; __device__ __forceinline__ u32x4 pack8(const float* f) { u32x4 w; w.x = pk2(f[0], f[1]); w.y = pk2(f[2], f[3]); w.z = pk2(f[4], f[5]); w.w = pk2(f[6], f[7]); return w; }
;     __device__ __forceinline__ void operator()(const Acc& acc, const Unit& u, int wr, int wc, int fr, int fq) const {
;     ...
;         for (int m = 0; m < 4; ++m) { const size_t row = (size_t)(row0 + m * 16); const bf16_t* pr = proj + row * NPROJ + col0;
;             float ga[8], gb[8], v[8]; unpack8(*(const u32x4*)(pr + C_GA), ga); unpack8(*(const u32x4*)(pr + C_GB), gb);
; #pragma unroll
;             for (int n = 0; n < 2; ++n) {
;                 const f32x4 A4 = {ga[4 * n], ga[4 * n + 1], ga[4 * n + 2], ga[4 * n + 3]}, B4 = {gb[4 * n], gb[4 * n + 1], gb[4 * n + 2], gb[4 * n + 3]};
;                 const f32x4 aa = A4 * (-1.4426950408889634f), ab = B4 * (-1.4426950408889634f);
;                 f32x4 ta, tb;
; #pragma unroll
;                 for (int j = 0; j < 4; ++j) { ta[j] = __builtin_amdgcn_exp2f(aa[j]); tb[j] = __builtin_amdgcn_exp2f(ab[j]); }
;                 ta = ta + 1.0f; tb = tb + 1.0f;
; #pragma unroll
;                 for (int j = 0; j < 4; ++j) { ta[j] = __builtin_amdgcn_rcpf(ta[j]); tb[j] = __builtin_amdgcn_rcpf(tb[j]); }
;                 const f32x4 r = acc[0][0][m][n] * ta + acc[1][1][m][n] * tb;
; #pragma unroll
;                 for (int j = 0; j < 4; ++j) v[4 * n + j] = r[j]; }
;             *(u32x4*)(O + row * DM + col0) = pack8(v); }
	v_mov_b32_e32 v48, v186
	v_mov_b32_e32 v49, v187
	v_mov_b32_e32 v50, v188
	v_mov_b32_e32 v51, v189
	s_nop 0
	v_addc_co_u32_e32 v53, vcc, 0, v53, vcc
	v_mov_b32_e32 v52, v190
	v_mov_b32_e32 v53, v191
	v_mov_b32_e32 v54, v192
	v_mov_b32_e32 v55, v193
	v_lshlrev_b32_e32 v59, 16, v49
	v_and_b32_e32 v49, 0xffff0000, v49
	v_lshlrev_b32_e32 v58, 16, v48
	v_lshlrev_b32_e32 v63, 16, v53
	v_and_b32_e32 v53, 0xffff0000, v53
	v_lshlrev_b32_e32 v62, 16, v52
	v_and_b32_e32 v52, 0xffff0000, v52
	v_lshlrev_b32_e32 v83, 16, v54
	v_and_b32_e32 v54, 0xffff0000, v54
	v_lshlrev_b32_e32 v94, 16, v55
	v_and_b32_e32 v55, 0xffff0000, v55
	v_mul_f32_e32 v63, 0xbfb8aa3b, v63
	v_mul_f32_e32 v97, 0xbfb8aa3b, v53
	v_and_b32_e32 v48, 0xffff0000, v48
	v_lshlrev_b32_e32 v60, 16, v50
	v_and_b32_e32 v50, 0xffff0000, v50
	v_lshlrev_b32_e32 v61, 16, v51
	v_and_b32_e32 v51, 0xffff0000, v51
	v_mul_f32_e32 v62, 0xbfb8aa3b, v62
	v_mul_f32_e32 v52, 0xbfb8aa3b, v52
	v_mul_f32_e32 v59, 0xbfb8aa3b, v59
	v_mul_f32_e32 v96, 0xbfb8aa3b, v49
	v_mul_f32_e32 v99, 0xbfb8aa3b, v54
	v_mul_f32_e32 v102, 0xbfb8aa3b, v55
	v_exp_f32_e32 v54, v63
	v_exp_f32_e32 v55, v97
	v_mul_f32_e32 v58, 0xbfb8aa3b, v58
	v_mul_f32_e32 v95, 0xbfb8aa3b, v48
	v_mul_f32_e32 v98, 0xbfb8aa3b, v50
	v_mul_f32_e32 v101, 0xbfb8aa3b, v51
	v_exp_f32_e32 v50, v62
	v_exp_f32_e32 v51, v52
	v_exp_f32_e32 v52, v59
	v_exp_f32_e32 v53, v96
	v_exp_f32_e32 v48, v58
	v_exp_f32_e32 v49, v95
	v_mul_f32_e32 v60, 0xbfb8aa3b, v60
	v_mul_f32_e32 v83, 0xbfb8aa3b, v83
	v_mul_f32_e32 v100, 0xbfb8aa3b, v61
	v_mul_f32_e32 v94, 0xbfb8aa3b, v94
	v_exp_f32_e32 v58, v60
	v_exp_f32_e32 v60, v83
	v_exp_f32_e32 v61, v99
	v_pk_add_f32 v[54:55], v[54:55], 1.0 op_sel_hi:[1,0]
	v_exp_f32_e32 v59, v98
	v_exp_f32_e32 v94, v94
	v_exp_f32_e32 v95, v102
	v_pk_add_f32 v[52:53], v[52:53], 1.0 op_sel_hi:[1,0]
	v_pk_add_f32 v[50:51], v[50:51], 1.0 op_sel_hi:[1,0]
	v_rcp_f32_e32 v54, v54
	v_rcp_f32_e32 v55, v55
	v_exp_f32_e32 v62, v100
	v_exp_f32_e32 v63, v101
	v_pk_add_f32 v[48:49], v[48:49], 1.0 op_sel_hi:[1,0]
	v_rcp_f32_e32 v50, v50
	v_rcp_f32_e32 v51, v51
	v_rcp_f32_e32 v52, v52
	v_rcp_f32_e32 v53, v53
	v_rcp_f32_e32 v48, v48
	v_rcp_f32_e32 v49, v49
	v_pk_add_f32 v[60:61], v[60:61], 1.0 op_sel_hi:[1,0]
	v_pk_add_f32 v[58:59], v[58:59], 1.0 op_sel_hi:[1,0]
	v_pk_add_f32 v[94:95], v[94:95], 1.0 op_sel_hi:[1,0]
	v_rcp_f32_e32 v60, v60
	v_pk_mul_f32 v[38:39], v[38:39], v[54:55]
	v_rcp_f32_e32 v61, v61
	v_pk_add_f32 v[62:63], v[62:63], 1.0 op_sel_hi:[1,0]
	v_rcp_f32_e32 v58, v58
	v_rcp_f32_e32 v59, v59
	v_pk_mul_f32 v[36:37], v[36:37], v[50:51]
	v_pk_fma_f32 v[38:39], v[46:47], v[52:53], v[38:39]
	v_rcp_f32_e32 v46, v94
	v_rcp_f32_e32 v47, v95
	v_pk_fma_f32 v[36:37], v[44:45], v[48:49], v[36:37]
	v_rcp_f32_e32 v44, v62
	v_rcp_f32_e32 v45, v63
	v_pk_mul_f32 v[32:33], v[32:33], v[60:61]
	s_nop 0
	v_pk_fma_f32 v[40:41], v[40:41], v[58:59], v[32:33]
	v_pk_mul_f32 v[32:33], v[34:35], v[46:47]
	v_cvt_pk_bf16_f32 v34, v40, v41
	v_pk_fma_f32 v[42:43], v[42:43], v[44:45], v[32:33]
	v_cvt_pk_bf16_f32 v32, v36, v37
	v_lshlrev_b64 v[36:37], 12, v[56:57]
	v_lshl_add_u64 v[36:37], s[8:9], 0, v[36:37]
	v_cvt_pk_bf16_f32 v33, v38, v39
	v_cvt_pk_bf16_f32 v35, v42, v43
	v_lshl_add_u64 v[36:37], v[36:37], 0, v[80:81]
	v_or_b32_e32 v40, 32, v82
	global_store_dwordx4 v[36:37], v[32:35], off
	v_ashrrev_i32_e32 v41, 31, v40
	s_nop 0
	v_mad_i64_i32 v[32:33], s[26:27], v40, s49, v[84:85]
	v_lshl_add_u64 v[36:37], v[32:33], 0, v[80:81]
	v_add_co_u32_e32 v32, vcc, s42, v36
	s_nop 1
	v_addc_co_u32_e32 v33, vcc, 0, v37, vcc
	v_add_co_u32_e32 v36, vcc, s50, v36
	s_waitcnt vmcnt(4)
; __device__ __forceinline__ u32x4 pack8(const float* f) { u32x4 w; w.x = pk2(f[0], f[1]); w.y = pk2(f[2], f[3]); w.z = pk2(f[4], f[5]); w.w = pk2(f[6], f[7]); return w; }
; #define PG8_WAIT_V(n) asm volatile("s_waitcnt vmcnt(" #n ")" ::: "memory")
; #define PG8_BAR __builtin_amdgcn_s_barrier()
; template <class Epi, class Sched>
; __device__ __forceinline__ void gemm_phase(LAS unsigned char* lds, const Gemm g, const Sched& S, const Epi& E) {
;     ...
;     PG8_WAIT_V(0);
;     if (wr == 0) PG8_BAR;
;     PG8_BAR;
;     __device__ __forceinline__ void operator()(const Acc& acc, const Unit& u, int wr, int wc, int fr, int fq) const {
;     ...
;         for (int m = 0; m < 4; ++m) { const size_t row = (size_t)(row0 + m * 16); const bf16_t* pr = proj + row * NPROJ + col0;
;             float ga[8], gb[8], v[8]; unpack8(*(const u32x4*)(pr + C_GA), ga); unpack8(*(const u32x4*)(pr + C_GB), gb);
; #pragma unroll
;             for (int n = 0; n < 2; ++n) {
;                 const f32x4 A4 = {ga[4 * n], ga[4 * n + 1], ga[4 * n + 2], ga[4 * n + 3]}, B4 = {gb[4 * n], gb[4 * n + 1], gb[4 * n + 2], gb[4 * n + 3]};
;                 const f32x4 aa = A4 * (-1.4426950408889634f), ab = B4 * (-1.4426950408889634f);
;                 f32x4 ta, tb;
; #pragma unroll
;                 for (int j = 0; j < 4; ++j) { ta[j] = __builtin_amdgcn_exp2f(aa[j]); tb[j] = __builtin_amdgcn_exp2f(ab[j]); }
;                 ta = ta + 1.0f; tb = tb + 1.0f;
; #pragma unroll
;                 for (int j = 0; j < 4; ++j) { ta[j] = __builtin_amdgcn_rcpf(ta[j]); tb[j] = __builtin_amdgcn_rcpf(tb[j]); }
;                 const f32x4 r = acc[0][0][m][n] * ta + acc[1][1][m][n] * tb;
; #pragma unroll
;                 for (int j = 0; j < 4; ++j) v[4 * n + j] = r[j]; }
;             *(u32x4*)(O + row * DM + col0) = pack8(v); }
	v_mov_b32_e32 v32, v194
	v_mov_b32_e32 v33, v195
	v_mov_b32_e32 v34, v196
	v_mov_b32_e32 v35, v197
	s_nop 0
	v_addc_co_u32_e32 v37, vcc, 0, v37, vcc
	v_mov_b32_e32 v36, v198
	v_mov_b32_e32 v37, v199
	v_mov_b32_e32 v38, v200
	v_mov_b32_e32 v39, v201
	v_lshlrev_b32_e32 v43, 16, v33
	v_and_b32_e32 v33, 0xffff0000, v33
	v_lshlrev_b32_e32 v44, 16, v34
	v_lshlrev_b32_e32 v46, 16, v36
	v_and_b32_e32 v36, 0xffff0000, v36
	v_lshlrev_b32_e32 v47, 16, v37
	v_and_b32_e32 v37, 0xffff0000, v37
	v_and_b32_e32 v34, 0xffff0000, v34
	v_lshlrev_b32_e32 v45, 16, v35
	v_and_b32_e32 v35, 0xffff0000, v35
	v_lshlrev_b32_e32 v48, 16, v38
	v_and_b32_e32 v38, 0xffff0000, v38
	v_lshlrev_b32_e32 v49, 16, v39
	v_and_b32_e32 v39, 0xffff0000, v39
	v_mul_f32_e32 v46, 0xbfb8aa3b, v46
	v_mul_f32_e32 v36, 0xbfb8aa3b, v36
	v_mul_f32_e32 v47, 0xbfb8aa3b, v47
	v_mul_f32_e32 v52, 0xbfb8aa3b, v37
	v_lshlrev_b32_e32 v42, 16, v32
	v_and_b32_e32 v32, 0xffff0000, v32
	v_mul_f32_e32 v43, 0xbfb8aa3b, v43
	v_mul_f32_e32 v51, 0xbfb8aa3b, v33
	v_mul_f32_e32 v53, 0xbfb8aa3b, v34
	v_mul_f32_e32 v54, 0xbfb8aa3b, v38
	v_mul_f32_e32 v55, 0xbfb8aa3b, v35
	v_mul_f32_e32 v56, 0xbfb8aa3b, v39
	v_exp_f32_e32 v34, v46
	v_exp_f32_e32 v35, v36
	v_exp_f32_e32 v38, v47
	v_exp_f32_e32 v39, v52
	v_mul_f32_e32 v42, 0xbfb8aa3b, v42
	v_mul_f32_e32 v50, 0xbfb8aa3b, v32
	v_exp_f32_e32 v36, v43
	v_exp_f32_e32 v37, v51
	v_exp_f32_e32 v32, v42
	v_exp_f32_e32 v33, v50
	v_mul_f32_e32 v44, 0xbfb8aa3b, v44
	v_mul_f32_e32 v48, 0xbfb8aa3b, v48
	v_mul_f32_e32 v45, 0xbfb8aa3b, v45
	v_pk_add_f32 v[38:39], v[38:39], 1.0 op_sel_hi:[1,0]
	v_pk_add_f32 v[34:35], v[34:35], 1.0 op_sel_hi:[1,0]
	v_exp_f32_e32 v42, v44
	v_exp_f32_e32 v44, v48
	v_exp_f32_e32 v46, v45
	v_pk_add_f32 v[36:37], v[36:37], 1.0 op_sel_hi:[1,0]
	v_rcp_f32_e32 v34, v34
	v_rcp_f32_e32 v35, v35
	v_rcp_f32_e32 v38, v38
	v_rcp_f32_e32 v39, v39
	v_exp_f32_e32 v45, v54
	v_mul_f32_e32 v49, 0xbfb8aa3b, v49
	v_exp_f32_e32 v43, v53
	v_pk_add_f32 v[32:33], v[32:33], 1.0 op_sel_hi:[1,0]
	v_rcp_f32_e32 v36, v36
	v_rcp_f32_e32 v37, v37
	v_exp_f32_e32 v48, v49
	v_exp_f32_e32 v49, v56
	v_rcp_f32_e32 v32, v32
	v_rcp_f32_e32 v33, v33
	v_exp_f32_e32 v47, v55
	v_pk_mul_f32 v[24:25], v[24:25], v[34:35]
	v_pk_mul_f32 v[26:27], v[26:27], v[38:39]
	v_pk_add_f32 v[34:35], v[44:45], 1.0 op_sel_hi:[1,0]
	v_pk_fma_f32 v[26:27], v[30:31], v[36:37], v[26:27]
	v_pk_add_f32 v[30:31], v[42:43], 1.0 op_sel_hi:[1,0]
	v_rcp_f32_e32 v34, v34
	v_rcp_f32_e32 v35, v35
	v_pk_fma_f32 v[24:25], v[28:29], v[32:33], v[24:25]
	v_pk_add_f32 v[32:33], v[48:49], 1.0 op_sel_hi:[1,0]
	v_rcp_f32_e32 v30, v30
	v_rcp_f32_e32 v31, v31
	v_pk_add_f32 v[28:29], v[46:47], 1.0 op_sel_hi:[1,0]
	v_rcp_f32_e32 v32, v32
	v_rcp_f32_e32 v33, v33
	v_rcp_f32_e32 v28, v28
	v_rcp_f32_e32 v29, v29
	v_pk_mul_f32 v[16:17], v[16:17], v[34:35]
	s_nop 0
	v_pk_fma_f32 v[20:21], v[20:21], v[30:31], v[16:17]
	v_pk_mul_f32 v[16:17], v[18:19], v[32:33]
	v_cvt_pk_bf16_f32 v18, v20, v21
	v_lshlrev_b64 v[20:21], 12, v[40:41]
	v_pk_fma_f32 v[22:23], v[22:23], v[28:29], v[16:17]
	v_lshl_add_u64 v[20:21], s[8:9], 0, v[20:21]
	v_cvt_pk_bf16_f32 v16, v24, v25
	v_cvt_pk_bf16_f32 v17, v26, v27
	v_cvt_pk_bf16_f32 v19, v22, v23
	v_lshl_add_u64 v[20:21], v[20:21], 0, v[80:81]
	v_or_b32_e32 v24, 48, v82
	global_store_dwordx4 v[20:21], v[16:19], off
	v_ashrrev_i32_e32 v25, 31, v24
	s_nop 0
	v_mad_i64_i32 v[16:17], s[26:27], v24, s49, v[84:85]
	v_lshl_add_u64 v[20:21], v[16:17], 0, v[80:81]
	v_add_co_u32_e32 v16, vcc, s42, v20
	s_mov_b64 s[26:27], s[20:21]
	s_nop 0
	v_addc_co_u32_e32 v17, vcc, 0, v21, vcc
	v_add_co_u32_e32 v20, vcc, s50, v20
	s_waitcnt vmcnt(3)
	v_mov_b32_e32 v16, v202
	v_mov_b32_e32 v17, v203
	v_mov_b32_e32 v18, v204
	v_mov_b32_e32 v19, v205
	s_nop 0
	v_addc_co_u32_e32 v21, vcc, 0, v21, vcc
	v_mov_b32_e32 v20, v206
	v_mov_b32_e32 v21, v207
	v_mov_b32_e32 v22, v208
	v_mov_b32_e32 v23, v209
	s_and_b64 vcc, exec, s[6:7]
	v_lshlrev_b32_e32 v29, 16, v19
	v_and_b32_e32 v30, 0xffff0000, v19
	v_lshlrev_b32_e32 v26, 16, v16
	v_lshlrev_b32_e32 v19, 16, v20
	v_and_b32_e32 v20, 0xffff0000, v20
	v_and_b32_e32 v16, 0xffff0000, v16
	v_lshlrev_b32_e32 v28, 16, v18
	v_and_b32_e32 v18, 0xffff0000, v18
	v_lshlrev_b32_e32 v31, 16, v21
	v_and_b32_e32 v21, 0xffff0000, v21
	v_mul_f32_e32 v19, 0xbfb8aa3b, v19
	v_mul_f32_e32 v20, 0xbfb8aa3b, v20
	v_lshlrev_b32_e32 v27, 16, v17
	v_and_b32_e32 v17, 0xffff0000, v17
	v_lshlrev_b32_e32 v32, 16, v22
	v_and_b32_e32 v22, 0xffff0000, v22
	v_lshlrev_b32_e32 v33, 16, v23
	v_and_b32_e32 v34, 0xffff0000, v23
	v_mul_f32_e32 v23, 0xbfb8aa3b, v26
	v_mul_f32_e32 v26, 0xbfb8aa3b, v16
	v_mul_f32_e32 v31, 0xbfb8aa3b, v31
	v_mul_f32_e32 v36, 0xbfb8aa3b, v21
	v_mul_f32_e32 v37, 0xbfb8aa3b, v18
	v_exp_f32_e32 v18, v19
	v_exp_f32_e32 v19, v20
	v_mul_f32_e32 v27, 0xbfb8aa3b, v27
	v_mul_f32_e32 v35, 0xbfb8aa3b, v17
	v_mul_f32_e32 v38, 0xbfb8aa3b, v22
	v_exp_f32_e32 v16, v23
	v_exp_f32_e32 v17, v26
	v_exp_f32_e32 v22, v31
	v_exp_f32_e32 v23, v36
	v_exp_f32_e32 v20, v27
	v_exp_f32_e32 v21, v35
	v_pk_add_f32 v[18:19], v[18:19], 1.0 op_sel_hi:[1,0]
	v_pk_add_f32 v[16:17], v[16:17], 1.0 op_sel_hi:[1,0]
	v_pk_add_f32 v[22:23], v[22:23], 1.0 op_sel_hi:[1,0]
	v_rcp_f32_e32 v18, v18
	v_rcp_f32_e32 v19, v19
	v_pk_add_f32 v[20:21], v[20:21], 1.0 op_sel_hi:[1,0]
	v_rcp_f32_e32 v16, v16
	v_rcp_f32_e32 v17, v17
	v_rcp_f32_e32 v22, v22
	v_rcp_f32_e32 v23, v23
	v_rcp_f32_e32 v20, v20
	v_rcp_f32_e32 v21, v21
	v_mul_f32_e32 v28, 0xbfb8aa3b, v28
	v_mul_f32_e32 v32, 0xbfb8aa3b, v32
	v_pk_mul_f32 v[8:9], v[8:9], v[18:19]
	v_exp_f32_e32 v26, v28
	v_exp_f32_e32 v28, v32
	v_pk_mul_f32 v[10:11], v[10:11], v[22:23]
	v_pk_fma_f32 v[8:9], v[12:13], v[16:17], v[8:9]
	v_mul_f32_e32 v12, 0xbfb8aa3b, v29
	v_exp_f32_e32 v29, v38
	v_exp_f32_e32 v27, v37
	v_pk_fma_f32 v[10:11], v[14:15], v[20:21], v[10:11]
	v_mul_f32_e32 v13, 0xbfb8aa3b, v33
	v_mul_f32_e32 v15, 0xbfb8aa3b, v34
	v_exp_f32_e32 v14, v13
	v_mul_f32_e32 v13, 0xbfb8aa3b, v30
	v_exp_f32_e32 v15, v15
	v_exp_f32_e32 v12, v12
	v_exp_f32_e32 v13, v13
	v_pk_add_f32 v[18:19], v[28:29], 1.0 op_sel_hi:[1,0]
	v_pk_add_f32 v[16:17], v[26:27], 1.0 op_sel_hi:[1,0]
	v_rcp_f32_e32 v18, v18
	v_rcp_f32_e32 v19, v19
	v_pk_add_f32 v[14:15], v[14:15], 1.0 op_sel_hi:[1,0]
	v_rcp_f32_e32 v16, v16
	v_rcp_f32_e32 v17, v17
	v_pk_add_f32 v[12:13], v[12:13], 1.0 op_sel_hi:[1,0]
	v_rcp_f32_e32 v14, v14
	v_rcp_f32_e32 v15, v15
	v_rcp_f32_e32 v12, v12
	v_rcp_f32_e32 v13, v13
	v_pk_mul_f32 v[0:1], v[0:1], v[18:19]
	s_nop 0
	v_pk_fma_f32 v[4:5], v[4:5], v[16:17], v[0:1]
	v_pk_mul_f32 v[0:1], v[2:3], v[14:15]
	v_cvt_pk_bf16_f32 v2, v4, v5
	v_lshlrev_b64 v[4:5], 12, v[24:25]
	v_pk_fma_f32 v[6:7], v[6:7], v[12:13], v[0:1]
	v_lshl_add_u64 v[4:5], s[8:9], 0, v[4:5]
	v_cvt_pk_bf16_f32 v0, v8, v9
	v_cvt_pk_bf16_f32 v1, v10, v11
	v_cvt_pk_bf16_f32 v3, v6, v7
	v_lshl_add_u64 v[4:5], v[4:5], 0, v[80:81]
	global_store_dwordx4 v[4:5], v[0:3], off
	s_cbranch_vccz .LBB0_1382
	s_waitcnt vmcnt(0)
	s_cmpk_gt_u32 s3, 0xff
	s_cbranch_scc1 .LBB0_1389
	s_barrier
